# SwiGLU GEMM epilogue rewritten: packed f32 scale and +1, exp/rcp chains pipelined over 4 register pairs (no hazard nops), 32-bit offset + scalar base stores
# speedup vs baseline: 1.0012x; 1.0012x over previous
; __device__ __forceinline__ bf16x8 pack8(f32x4 a, f32x4 b) { u32x4 w = {pk2(a[0], a[1]), pk2(a[2], a[3]), pk2(b[0], b[1]), pk2(b[2], b[3])}; return __builtin_bit_cast(bf16x8, w); }
; __device__ __forceinline__ float sigmoidf_(float v) { return __builtin_amdgcn_rcpf(1.0f + __builtin_amdgcn_exp2f(v * -1.4426950408889634f)); }
;     __device__ __forceinline__ void operator()(const f32x4 (&acc)[2][2][4][2], const Unit& u, int wr, int wc, int fr, int fq) const {
; #pragma unroll
;         for (int ai = 0; ai < 2; ++ai)
; #pragma unroll
;             for (int m = 0; m < 4; ++m) {
;                 const int row = u.pm * 256 + ai * 128 + wr * 64 + m * 16 + fr, f0 = u.pn * 128 + wc * 32 + 8 * fq;
;                 const f32x4 g0 = acc[ai][0][m][0], g1 = acc[ai][0][m][1], u0 = acc[ai][1][m][0], u1 = acc[ai][1][m][1];
;                 f32x4 o0, o1;
; #pragma unroll
;                 for (int e = 0; e < 4; ++e) { o0[e] = g0[e] * sigmoidf_(g0[e]) * u0[e]; o1[e] = g1[e] * sigmoidf_(g1[e]) * u1[e]; }
;                 *(bf16x8*)(H + (size_t)row * FF + f0) = pack8(o0, o1);
;             }
;     }
.LBB0_1707:
	v_lshl_or_b32 v144, s69, 7, v140
	v_lshl_add_u32 v142, s46, 8, v138
	v_mov_b32_e32 v150, 0xbfb8aa3b
	v_mov_b32_e32 v151, 0xbfb8aa3b
	v_mov_b32_e32 v152, 1.0
	v_mov_b32_e32 v153, 1.0
	v_lshlrev_b32_e32 v146, 1, v144
	v_add_u32_e32 v147, 0x0, v142
	v_pk_mul_f32 v[154:155], v[124:125], v[150:151]
	v_pk_mul_f32 v[156:157], v[126:127], v[150:151]
	v_pk_mul_f32 v[158:159], v[116:117], v[150:151]
	v_pk_mul_f32 v[160:161], v[118:119], v[150:151]
	v_mad_u32_u24 v170, v147, s2, v146
	v_exp_f32_e32 v154, v154
	v_exp_f32_e32 v155, v155
	v_exp_f32_e32 v156, v156
	v_exp_f32_e32 v157, v157
	v_exp_f32_e32 v158, v158
	v_exp_f32_e32 v159, v159
	v_exp_f32_e32 v160, v160
	v_exp_f32_e32 v161, v161
	v_pk_add_f32 v[154:155], v[154:155], v[152:153]
	v_pk_add_f32 v[156:157], v[156:157], v[152:153]
	v_pk_add_f32 v[158:159], v[158:159], v[152:153]
	v_pk_add_f32 v[160:161], v[160:161], v[152:153]
	v_rcp_f32_e32 v154, v154
	v_rcp_f32_e32 v155, v155
	v_rcp_f32_e32 v156, v156
	v_rcp_f32_e32 v157, v157
	v_rcp_f32_e32 v158, v158
	v_rcp_f32_e32 v159, v159
	v_rcp_f32_e32 v160, v160
	v_rcp_f32_e32 v161, v161
	v_pk_mul_f32 v[124:125], v[124:125], v[154:155]
	v_pk_mul_f32 v[126:127], v[126:127], v[156:157]
	v_pk_mul_f32 v[116:117], v[116:117], v[158:159]
	v_pk_mul_f32 v[118:119], v[118:119], v[160:161]
	v_pk_mul_f32 v[120:121], v[124:125], v[120:121]
	v_pk_mul_f32 v[122:123], v[126:127], v[122:123]
	v_pk_mul_f32 v[112:113], v[116:117], v[112:113]
	v_pk_mul_f32 v[114:115], v[118:119], v[114:115]
	v_cvt_pk_bf16_f32 v162, v120, v121
	v_cvt_pk_bf16_f32 v163, v122, v123
	v_cvt_pk_bf16_f32 v164, v112, v113
	v_cvt_pk_bf16_f32 v165, v114, v115
	s_nop 0
	global_store_dwordx4 v170, v[162:165], s[14:15]
	v_add_u32_e32 v147, 0x10, v142
	v_pk_mul_f32 v[154:155], v[108:109], v[150:151]
	v_pk_mul_f32 v[156:157], v[110:111], v[150:151]
	v_pk_mul_f32 v[158:159], v[100:101], v[150:151]
	v_pk_mul_f32 v[160:161], v[102:103], v[150:151]
	v_mad_u32_u24 v171, v147, s2, v146
	v_exp_f32_e32 v154, v154
	v_exp_f32_e32 v155, v155
	v_exp_f32_e32 v156, v156
	v_exp_f32_e32 v157, v157
	v_exp_f32_e32 v158, v158
	v_exp_f32_e32 v159, v159
	v_exp_f32_e32 v160, v160
	v_exp_f32_e32 v161, v161
	v_pk_add_f32 v[154:155], v[154:155], v[152:153]
	v_pk_add_f32 v[156:157], v[156:157], v[152:153]
	v_pk_add_f32 v[158:159], v[158:159], v[152:153]
	v_pk_add_f32 v[160:161], v[160:161], v[152:153]
	v_rcp_f32_e32 v154, v154
	v_rcp_f32_e32 v155, v155
	v_rcp_f32_e32 v156, v156
	v_rcp_f32_e32 v157, v157
	v_rcp_f32_e32 v158, v158
	v_rcp_f32_e32 v159, v159
	v_rcp_f32_e32 v160, v160
	v_rcp_f32_e32 v161, v161
	v_pk_mul_f32 v[108:109], v[108:109], v[154:155]
	v_pk_mul_f32 v[110:111], v[110:111], v[156:157]
	v_pk_mul_f32 v[100:101], v[100:101], v[158:159]
	v_pk_mul_f32 v[102:103], v[102:103], v[160:161]
	v_pk_mul_f32 v[104:105], v[108:109], v[104:105]
	v_pk_mul_f32 v[106:107], v[110:111], v[106:107]
	v_pk_mul_f32 v[96:97], v[100:101], v[96:97]
	v_pk_mul_f32 v[98:99], v[102:103], v[98:99]
	v_cvt_pk_bf16_f32 v166, v104, v105
	v_cvt_pk_bf16_f32 v167, v106, v107
	v_cvt_pk_bf16_f32 v168, v96, v97
	v_cvt_pk_bf16_f32 v169, v98, v99
	s_nop 0
	global_store_dwordx4 v171, v[166:169], s[14:15]
	v_add_u32_e32 v147, 0x20, v142
	v_pk_mul_f32 v[154:155], v[92:93], v[150:151]
	v_pk_mul_f32 v[156:157], v[94:95], v[150:151]
	v_pk_mul_f32 v[158:159], v[84:85], v[150:151]
	v_pk_mul_f32 v[160:161], v[86:87], v[150:151]
	v_mad_u32_u24 v172, v147, s2, v146
	v_exp_f32_e32 v154, v154
	v_exp_f32_e32 v155, v155
	v_exp_f32_e32 v156, v156
	v_exp_f32_e32 v157, v157
	v_exp_f32_e32 v158, v158
	v_exp_f32_e32 v159, v159
	v_exp_f32_e32 v160, v160
	v_exp_f32_e32 v161, v161
	v_pk_add_f32 v[154:155], v[154:155], v[152:153]
	v_pk_add_f32 v[156:157], v[156:157], v[152:153]
	v_pk_add_f32 v[158:159], v[158:159], v[152:153]
	v_pk_add_f32 v[160:161], v[160:161], v[152:153]
	v_rcp_f32_e32 v154, v154
	v_rcp_f32_e32 v155, v155
	v_rcp_f32_e32 v156, v156
	v_rcp_f32_e32 v157, v157
	v_rcp_f32_e32 v158, v158
	v_rcp_f32_e32 v159, v159
	v_rcp_f32_e32 v160, v160
	v_rcp_f32_e32 v161, v161
	v_pk_mul_f32 v[92:93], v[92:93], v[154:155]
	v_pk_mul_f32 v[94:95], v[94:95], v[156:157]
	v_pk_mul_f32 v[84:85], v[84:85], v[158:159]
	v_pk_mul_f32 v[86:87], v[86:87], v[160:161]
	v_pk_mul_f32 v[88:89], v[92:93], v[88:89]
	v_pk_mul_f32 v[90:91], v[94:95], v[90:91]
	v_pk_mul_f32 v[80:81], v[84:85], v[80:81]
	v_pk_mul_f32 v[82:83], v[86:87], v[82:83]
	v_cvt_pk_bf16_f32 v162, v88, v89
	v_cvt_pk_bf16_f32 v163, v90, v91
	v_cvt_pk_bf16_f32 v164, v80, v81
	v_cvt_pk_bf16_f32 v165, v82, v83
	s_nop 0
	global_store_dwordx4 v172, v[162:165], s[14:15]
	v_add_u32_e32 v147, 0x30, v142
	v_pk_mul_f32 v[154:155], v[76:77], v[150:151]
	v_pk_mul_f32 v[156:157], v[78:79], v[150:151]
	v_pk_mul_f32 v[158:159], v[68:69], v[150:151]
	v_pk_mul_f32 v[160:161], v[70:71], v[150:151]
	v_mad_u32_u24 v173, v147, s2, v146
	v_exp_f32_e32 v154, v154
	v_exp_f32_e32 v155, v155
	v_exp_f32_e32 v156, v156
	v_exp_f32_e32 v157, v157
	v_exp_f32_e32 v158, v158
	v_exp_f32_e32 v159, v159
	v_exp_f32_e32 v160, v160
	v_exp_f32_e32 v161, v161
	v_pk_add_f32 v[154:155], v[154:155], v[152:153]
	v_pk_add_f32 v[156:157], v[156:157], v[152:153]
	v_pk_add_f32 v[158:159], v[158:159], v[152:153]
	v_pk_add_f32 v[160:161], v[160:161], v[152:153]
	v_rcp_f32_e32 v154, v154
	v_rcp_f32_e32 v155, v155
	v_rcp_f32_e32 v156, v156
	v_rcp_f32_e32 v157, v157
	v_rcp_f32_e32 v158, v158
	v_rcp_f32_e32 v159, v159
	v_rcp_f32_e32 v160, v160
	v_rcp_f32_e32 v161, v161
	v_pk_mul_f32 v[76:77], v[76:77], v[154:155]
	v_pk_mul_f32 v[78:79], v[78:79], v[156:157]
	v_pk_mul_f32 v[68:69], v[68:69], v[158:159]
	v_pk_mul_f32 v[70:71], v[70:71], v[160:161]
	v_pk_mul_f32 v[72:73], v[76:77], v[72:73]
; __device__ __forceinline__ bf16x8 pack8(f32x4 a, f32x4 b) { u32x4 w = {pk2(a[0], a[1]), pk2(a[2], a[3]), pk2(b[0], b[1]), pk2(b[2], b[3])}; return __builtin_bit_cast(bf16x8, w); }
; __device__ __forceinline__ float sigmoidf_(float v) { return __builtin_amdgcn_rcpf(1.0f + __builtin_amdgcn_exp2f(v * -1.4426950408889634f)); }
; template <class Epi, class Sched, bool ALIGN_EPI = false, bool SP2 = false>
; __device__ __forceinline__ void gemm_phase(PG8_LAS unsigned char* lds, const Gemm g, const Sched& S, const Epi& E) {
;     ...
;         if constexpr (!Epi::AFTER_DRAIN) { E(acc, cur, wr, wc, fr, fq); S.done(cur); }
;         if (!has_next) break;
;     __device__ __forceinline__ void operator()(const f32x4 (&acc)[2][2][4][2], const Unit& u, int wr, int wc, int fr, int fq) const {
; #pragma unroll
;         for (int ai = 0; ai < 2; ++ai)
; #pragma unroll
;             for (int m = 0; m < 4; ++m) {
;                 const int row = u.pm * 256 + ai * 128 + wr * 64 + m * 16 + fr, f0 = u.pn * 128 + wc * 32 + 8 * fq;
;                 const f32x4 g0 = acc[ai][0][m][0], g1 = acc[ai][0][m][1], u0 = acc[ai][1][m][0], u1 = acc[ai][1][m][1];
;                 f32x4 o0, o1;
; #pragma unroll
;                 for (int e = 0; e < 4; ++e) { o0[e] = g0[e] * sigmoidf_(g0[e]) * u0[e]; o1[e] = g1[e] * sigmoidf_(g1[e]) * u1[e]; }
;                 *(bf16x8*)(H + (size_t)row * FF + f0) = pack8(o0, o1);
;             }
;     }
	v_pk_mul_f32 v[74:75], v[78:79], v[74:75]
	v_pk_mul_f32 v[64:65], v[68:69], v[64:65]
	v_pk_mul_f32 v[66:67], v[70:71], v[66:67]
	v_cvt_pk_bf16_f32 v166, v72, v73
	v_cvt_pk_bf16_f32 v167, v74, v75
	v_cvt_pk_bf16_f32 v168, v64, v65
	v_cvt_pk_bf16_f32 v169, v66, v67
	s_nop 0
	global_store_dwordx4 v173, v[166:169], s[14:15]
	v_add_u32_e32 v147, 0x80, v142
	v_pk_mul_f32 v[154:155], v[60:61], v[150:151]
	v_pk_mul_f32 v[156:157], v[62:63], v[150:151]
	v_pk_mul_f32 v[158:159], v[52:53], v[150:151]
	v_pk_mul_f32 v[160:161], v[54:55], v[150:151]
	v_mad_u32_u24 v174, v147, s2, v146
	v_exp_f32_e32 v154, v154
	v_exp_f32_e32 v155, v155
	v_exp_f32_e32 v156, v156
	v_exp_f32_e32 v157, v157
	v_exp_f32_e32 v158, v158
	v_exp_f32_e32 v159, v159
	v_exp_f32_e32 v160, v160
	v_exp_f32_e32 v161, v161
	v_pk_add_f32 v[154:155], v[154:155], v[152:153]
	v_pk_add_f32 v[156:157], v[156:157], v[152:153]
	v_pk_add_f32 v[158:159], v[158:159], v[152:153]
	v_pk_add_f32 v[160:161], v[160:161], v[152:153]
	v_rcp_f32_e32 v154, v154
	v_rcp_f32_e32 v155, v155
	v_rcp_f32_e32 v156, v156
	v_rcp_f32_e32 v157, v157
	v_rcp_f32_e32 v158, v158
	v_rcp_f32_e32 v159, v159
	v_rcp_f32_e32 v160, v160
	v_rcp_f32_e32 v161, v161
	v_pk_mul_f32 v[60:61], v[60:61], v[154:155]
	v_pk_mul_f32 v[62:63], v[62:63], v[156:157]
	v_pk_mul_f32 v[52:53], v[52:53], v[158:159]
	v_pk_mul_f32 v[54:55], v[54:55], v[160:161]
	v_pk_mul_f32 v[56:57], v[60:61], v[56:57]
	v_pk_mul_f32 v[58:59], v[62:63], v[58:59]
	v_pk_mul_f32 v[48:49], v[52:53], v[48:49]
	v_pk_mul_f32 v[50:51], v[54:55], v[50:51]
	v_cvt_pk_bf16_f32 v162, v56, v57
	v_cvt_pk_bf16_f32 v163, v58, v59
	v_cvt_pk_bf16_f32 v164, v48, v49
	v_cvt_pk_bf16_f32 v165, v50, v51
	s_nop 0
	global_store_dwordx4 v174, v[162:165], s[14:15]
	v_add_u32_e32 v147, 0x90, v142
	v_pk_mul_f32 v[154:155], v[44:45], v[150:151]
	v_pk_mul_f32 v[156:157], v[46:47], v[150:151]
	v_pk_mul_f32 v[158:159], v[36:37], v[150:151]
	v_pk_mul_f32 v[160:161], v[38:39], v[150:151]
	v_mad_u32_u24 v175, v147, s2, v146
	v_exp_f32_e32 v154, v154
	v_exp_f32_e32 v155, v155
	v_exp_f32_e32 v156, v156
	v_exp_f32_e32 v157, v157
	v_exp_f32_e32 v158, v158
	v_exp_f32_e32 v159, v159
	v_exp_f32_e32 v160, v160
	v_exp_f32_e32 v161, v161
	v_pk_add_f32 v[154:155], v[154:155], v[152:153]
	v_pk_add_f32 v[156:157], v[156:157], v[152:153]
	v_pk_add_f32 v[158:159], v[158:159], v[152:153]
	v_pk_add_f32 v[160:161], v[160:161], v[152:153]
	v_rcp_f32_e32 v154, v154
	v_rcp_f32_e32 v155, v155
	v_rcp_f32_e32 v156, v156
	v_rcp_f32_e32 v157, v157
	v_rcp_f32_e32 v158, v158
	v_rcp_f32_e32 v159, v159
	v_rcp_f32_e32 v160, v160
	v_rcp_f32_e32 v161, v161
	v_pk_mul_f32 v[44:45], v[44:45], v[154:155]
	v_pk_mul_f32 v[46:47], v[46:47], v[156:157]
	v_pk_mul_f32 v[36:37], v[36:37], v[158:159]
	v_pk_mul_f32 v[38:39], v[38:39], v[160:161]
	v_pk_mul_f32 v[40:41], v[44:45], v[40:41]
	v_pk_mul_f32 v[42:43], v[46:47], v[42:43]
	v_pk_mul_f32 v[32:33], v[36:37], v[32:33]
	v_pk_mul_f32 v[34:35], v[38:39], v[34:35]
	v_cvt_pk_bf16_f32 v166, v40, v41
	v_cvt_pk_bf16_f32 v167, v42, v43
	v_cvt_pk_bf16_f32 v168, v32, v33
	v_cvt_pk_bf16_f32 v169, v34, v35
	s_nop 0
	global_store_dwordx4 v175, v[166:169], s[14:15]
	v_add_u32_e32 v147, 0xa0, v142
	v_pk_mul_f32 v[154:155], v[28:29], v[150:151]
	v_pk_mul_f32 v[156:157], v[30:31], v[150:151]
	v_pk_mul_f32 v[158:159], v[20:21], v[150:151]
	v_pk_mul_f32 v[160:161], v[22:23], v[150:151]
	v_mad_u32_u24 v176, v147, s2, v146
	v_exp_f32_e32 v154, v154
	v_exp_f32_e32 v155, v155
	v_exp_f32_e32 v156, v156
	v_exp_f32_e32 v157, v157
	v_exp_f32_e32 v158, v158
	v_exp_f32_e32 v159, v159
	v_exp_f32_e32 v160, v160
	v_exp_f32_e32 v161, v161
	v_pk_add_f32 v[154:155], v[154:155], v[152:153]
	v_pk_add_f32 v[156:157], v[156:157], v[152:153]
	v_pk_add_f32 v[158:159], v[158:159], v[152:153]
	v_pk_add_f32 v[160:161], v[160:161], v[152:153]
	v_rcp_f32_e32 v154, v154
	v_rcp_f32_e32 v155, v155
	v_rcp_f32_e32 v156, v156
	v_rcp_f32_e32 v157, v157
	v_rcp_f32_e32 v158, v158
	v_rcp_f32_e32 v159, v159
	v_rcp_f32_e32 v160, v160
	v_rcp_f32_e32 v161, v161
	v_pk_mul_f32 v[28:29], v[28:29], v[154:155]
	v_pk_mul_f32 v[30:31], v[30:31], v[156:157]
	v_pk_mul_f32 v[20:21], v[20:21], v[158:159]
	v_pk_mul_f32 v[22:23], v[22:23], v[160:161]
	v_pk_mul_f32 v[24:25], v[28:29], v[24:25]
	v_pk_mul_f32 v[26:27], v[30:31], v[26:27]
	v_pk_mul_f32 v[16:17], v[20:21], v[16:17]
	v_pk_mul_f32 v[18:19], v[22:23], v[18:19]
	v_cvt_pk_bf16_f32 v162, v24, v25
	v_cvt_pk_bf16_f32 v163, v26, v27
	v_cvt_pk_bf16_f32 v164, v16, v17
	v_cvt_pk_bf16_f32 v165, v18, v19
	s_nop 0
	global_store_dwordx4 v176, v[162:165], s[14:15]
	v_add_u32_e32 v147, 0xb0, v142
	v_pk_mul_f32 v[154:155], v[12:13], v[150:151]
	v_pk_mul_f32 v[156:157], v[14:15], v[150:151]
	v_pk_mul_f32 v[158:159], v[4:5], v[150:151]
	v_pk_mul_f32 v[160:161], v[6:7], v[150:151]
	v_mad_u32_u24 v177, v147, s2, v146
	v_exp_f32_e32 v154, v154
	v_exp_f32_e32 v155, v155
	v_exp_f32_e32 v156, v156
	v_exp_f32_e32 v157, v157
	v_exp_f32_e32 v158, v158
	v_exp_f32_e32 v159, v159
	v_exp_f32_e32 v160, v160
	v_exp_f32_e32 v161, v161
	v_pk_add_f32 v[154:155], v[154:155], v[152:153]
	v_pk_add_f32 v[156:157], v[156:157], v[152:153]
	v_pk_add_f32 v[158:159], v[158:159], v[152:153]
	v_pk_add_f32 v[160:161], v[160:161], v[152:153]
	v_rcp_f32_e32 v154, v154
	v_rcp_f32_e32 v155, v155
	v_rcp_f32_e32 v156, v156
	v_rcp_f32_e32 v157, v157
	v_rcp_f32_e32 v158, v158
	v_rcp_f32_e32 v159, v159
	v_rcp_f32_e32 v160, v160
	v_rcp_f32_e32 v161, v161
	v_pk_mul_f32 v[12:13], v[12:13], v[154:155]
	v_pk_mul_f32 v[14:15], v[14:15], v[156:157]
	v_pk_mul_f32 v[4:5], v[4:5], v[158:159]
	v_pk_mul_f32 v[6:7], v[6:7], v[160:161]
	v_pk_mul_f32 v[8:9], v[12:13], v[8:9]
	v_pk_mul_f32 v[10:11], v[14:15], v[10:11]
	v_pk_mul_f32 v[0:1], v[4:5], v[0:1]
	v_pk_mul_f32 v[2:3], v[6:7], v[2:3]
	v_cvt_pk_bf16_f32 v166, v8, v9
	v_cvt_pk_bf16_f32 v167, v10, v11
	v_cvt_pk_bf16_f32 v168, v0, v1
	v_cvt_pk_bf16_f32 v169, v2, v3
	s_nop 0
	global_store_dwordx4 v177, v[166:169], s[14:15]
	s_andn2_b64 vcc, exec, s[6:7]
	s_mov_b64 s[4:5], -1
	s_cbranch_vccnz .LBB0_1700
	s_andn2_b64 vcc, exec, s[12:13]
	s_cbranch_vccnz .LBB0_1699
	s_barrier
	s_branch .LBB0_1699
